# static priority 1 for waves 4-7 for the whole kernel on top of the no-flip GEMM loops
# baseline (speedup 1.0000x reference)
.LBB0_70:
	v_readlane_b32 s0, v253, 2
	v_readlane_b32 s1, v253, 3
	v_mov_b32_e32 v1, v0
	v_writelane_b32 v254, s0, 21
	s_load_dwordx4 s[64:67], s[0:1], 0xb0
	s_mov_b32 s81, s80
	v_mbcnt_lo_u32_b32 v1, -1, v1
	v_writelane_b32 v254, s1, 22
	v_mbcnt_hi_u32_b32 v1, -1, v1
	v_readlane_b32 s0, v253, 5
	s_cmp_lt_u32 s92, 1
	s_nop 0
	v_or_b32_e32 v170, s0, v1
	v_cmp_lt_u32_e32 vcc, 0xff, v170
	s_cbranch_vccz .Lprio_skip
	s_setprio 1
.Lprio_skip:
	v_readlane_b32 s0, v253, 0
	s_mov_b32 s83, s0
	v_readlane_b32 s1, v253, 1
	s_cbranch_scc1 .LBB0_124
	s_waitcnt vmcnt(0)
	v_cmp_eq_u32_e32 vcc, 0, v170
	s_waitcnt lgkmcnt(0)
	s_barrier
	s_and_saveexec_b64 s[0:1], vcc
	s_cbranch_execz .LBB0_123
	v_readlane_b32 s2, v254, 17
	s_waitcnt vmcnt(0) expcnt(0) lgkmcnt(0)
	s_nop 0
	v_mov_b32_e32 v1, s2
	ds_read_b32 v3, v1
	v_readlane_b32 s2, v254, 18
	s_waitcnt lgkmcnt(0)
	v_cmp_ne_u32_e32 vcc, 0, v3
	v_mov_b32_e32 v1, s2
	ds_read_b32 v2, v1
	s_cbranch_vccnz .LBB0_87
	s_mov_b32 s8, 1
	s_branch .LBB0_75
